# MLA loop: LDS-DMA pieces spread wider over the S0 chain (after MFMA 0,2,4,7,10)
# baseline (speedup 1.0000x reference)
.Lmla_skipv0_o:
	v_add_f32_e32 v212, v66, v212
	v_exp_f32_e32 v68, v68
	v_add_f32_e32 v212, v67, v212
	v_exp_f32_e32 v69, v69
	s_waitcnt lgkmcnt(3)
	v_mfma_f32_32x32x16_bf16 v[80:95], v[234:237], v[120:123], v[80:95]
	ds_read_b128 v[234:237], v190 offset:57344
	v_add_f32_e32 v212, v68, v212
	v_exp_f32_e32 v70, v70
	v_add_f32_e32 v212, v69, v212
	v_exp_f32_e32 v71, v71
	s_waitcnt lgkmcnt(3)
	v_mfma_f32_32x32x16_bf16 v[80:95], v[238:241], v[116:119], v[80:95]
	ds_read_b128 v[238:241], v191 offset:57344
	s_cmp_eq_u32 s58, 2
	s_cbranch_scc1 .Lmla_skipv1_o
	s_mov_b32 m0, s55
	v_lshl_add_u64 v[254:255], v[166:167], 1, s[100:101]
	global_load_lds_dwordx4 v[254:255], off
.Lmla_skipv1_o:
	v_add_f32_e32 v212, v70, v212
	v_exp_f32_e32 v72, v72
	v_add_f32_e32 v212, v71, v212
	v_exp_f32_e32 v73, v73
	s_waitcnt lgkmcnt(3)
	v_mfma_f32_32x32x16_bf16 v[80:95], v[242:245], v[112:115], v[80:95]
	ds_read_b128 v[242:245], v192 offset:57344
	v_add_f32_e32 v212, v72, v212
	v_exp_f32_e32 v74, v74
	v_add_f32_e32 v212, v73, v212
	v_exp_f32_e32 v75, v75
	s_waitcnt lgkmcnt(3)
	v_mfma_f32_32x32x16_bf16 v[80:95], v[230:233], v[108:111], v[80:95]
	v_add_u32_e32 v211, 0x6000, v203
	ds_read_b128 v[230:233], v211 offset:49152
	s_mov_b32 m0, s23
	v_lshl_add_u64 v[254:255], v[160:161], 1, s[16:17]
	global_load_lds_dwordx4 v[254:255], off
	v_add_f32_e32 v212, v74, v212
	v_exp_f32_e32 v76, v76
	v_add_f32_e32 v212, v75, v212
	v_exp_f32_e32 v77, v77
	s_waitcnt lgkmcnt(3)
	v_mfma_f32_32x32x16_bf16 v[80:95], v[234:237], v[104:107], v[80:95]
	v_add_u32_e32 v211, 0x6000, v204
	ds_read_b128 v[234:237], v211 offset:49152
	v_add_f32_e32 v212, v76, v212
	v_exp_f32_e32 v78, v78
	v_add_f32_e32 v212, v77, v212
	v_exp_f32_e32 v79, v79
	s_waitcnt lgkmcnt(3)
	v_mfma_f32_32x32x16_bf16 v[80:95], v[238:241], v[100:103], v[80:95]
	v_add_u32_e32 v211, 0x6000, v205
	ds_read_b128 v[238:241], v211 offset:49152
	v_add_f32_e32 v212, v78, v212
	v_add_f32_e32 v212, v79, v212
	v_mov_b32_e32 v213, v212
	s_waitcnt lgkmcnt(3)
	v_mfma_f32_32x32x16_bf16 v[80:95], v[242:245], v[96:99], v[80:95]
	v_add_u32_e32 v211, 0x6000, v206
	ds_read_b128 v[242:245], v211 offset:49152
	s_mov_b32 m0, s7
	v_lshl_add_u64 v[254:255], v[162:163], 1, s[16:17]
	global_load_lds_dwordx4 v[254:255], off
	v_cvt_pk_bf16_f32 v152, v64, v65
	v_cvt_pk_bf16_f32 v153, v66, v67
	v_cvt_pk_bf16_f32 v154, v68, v69
	s_waitcnt lgkmcnt(3)
	v_mfma_f32_32x32x16_bf16 v[80:95], v[230:233], v[128:131], v[80:95]
	v_add_u32_e32 v211, v209, v194
	ds_read_b128 v[230:233], v211 offset:8192
	v_cvt_pk_bf16_f32 v155, v70, v71
	v_cvt_pk_bf16_f32 v156, v72, v73
	v_cvt_pk_bf16_f32 v157, v74, v75
	s_waitcnt lgkmcnt(3)
	v_mfma_f32_32x32x16_bf16 v[80:95], v[234:237], v[132:135], v[80:95]
	v_add_u32_e32 v211, v209, v195
	ds_read_b128 v[234:237], v211 offset:8192
	v_cvt_pk_bf16_f32 v158, v76, v77
	v_cvt_pk_bf16_f32 v159, v78, v79
	v_permlane32_swap_b32_e32 v212, v213
	s_waitcnt lgkmcnt(3)
	v_mfma_f32_32x32x16_bf16 v[80:95], v[238:241], v[136:139], v[80:95]
	v_add_u32_e32 v211, v209, v196
	ds_read_b128 v[238:241], v211 offset:8192
	s_mov_b32 m0, s30
	v_mad_i64_i32 v[254:255], s[0:1], s0, v180, v[168:169]
	global_load_lds_dwordx4 v[254:255], off
	s_add_u32 s100, s16, 0x100
	s_addc_u32 s101, s17, 0
	v_add_f32_e32 v252, v212, v213
	v_fma_f32 v183, v207, v183, v252
	v_permlane32_swap_b32_e32 v152, v154
	s_waitcnt lgkmcnt(3)
	v_mfma_f32_32x32x16_bf16 v[80:95], v[242:245], v[140:143], v[80:95]
	v_add_u32_e32 v211, v209, v197
	ds_read_b128 v[242:245], v211 offset:8192
	v_permlane32_swap_b32_e32 v153, v155
	v_permlane32_swap_b32_e32 v156, v158
	v_permlane32_swap_b32_e32 v157, v159
	s_waitcnt lgkmcnt(3)
	v_mfma_f32_32x32x16_bf16 v[64:79], v[230:233], v[124:127], 0
	v_add_u32_e32 v211, v209, v198
	ds_read_b128 v[230:233], v211 offset:8192
	s_waitcnt lgkmcnt(3)
	v_mfma_f32_32x32x16_bf16 v[64:79], v[234:237], v[120:123], v[64:79]
	v_add_u32_e32 v211, v209, v199
	ds_read_b128 v[234:237], v211 offset:8192
	s_waitcnt lgkmcnt(3)
	v_mfma_f32_32x32x16_bf16 v[64:79], v[238:241], v[116:119], v[64:79]
	v_add_u32_e32 v211, v209, v200
	ds_read_b128 v[238:241], v211 offset:8192
	s_waitcnt lgkmcnt(3)
	v_mfma_f32_32x32x16_bf16 v[64:79], v[242:245], v[112:115], v[64:79]
	v_add_u32_e32 v211, v209, v201
	ds_read_b128 v[242:245], v211 offset:8192
	s_waitcnt lgkmcnt(3)
	v_mfma_f32_32x32x16_bf16 v[64:79], v[230:233], v[108:111], v[64:79]
	v_add_u32_e32 v211, 0x6000, v203
	ds_read_b128 v[230:233], v211 offset:53248
	s_waitcnt lgkmcnt(3)
	v_mfma_f32_32x32x16_bf16 v[64:79], v[234:237], v[104:107], v[64:79]
	v_add_u32_e32 v211, 0x6000, v204
	ds_read_b128 v[234:237], v211 offset:53248
	s_waitcnt lgkmcnt(3)
	v_mfma_f32_32x32x16_bf16 v[64:79], v[238:241], v[100:103], v[64:79]
	v_add_u32_e32 v211, 0x6000, v205
	ds_read_b128 v[238:241], v211 offset:53248
	v_max_f32_e32 v249, v80, v81
	v_max3_f32 v249, v249, v82, v83
	s_waitcnt lgkmcnt(3)
	v_mfma_f32_32x32x16_bf16 v[64:79], v[242:245], v[96:99], v[64:79]
	v_add_u32_e32 v211, 0x6000, v206
	ds_read_b128 v[242:245], v211 offset:53248
	v_max3_f32 v249, v249, v84, v85
	v_max3_f32 v249, v249, v86, v87
	s_waitcnt lgkmcnt(3)
	v_mfma_f32_32x32x16_bf16 v[64:79], v[230:233], v[128:131], v[64:79]
	ds_read_b64_tr_b16 v[214:215], v185
	ds_read_b64_tr_b16 v[216:217], v185 offset:2048
	v_max3_f32 v249, v249, v88, v89
	v_max3_f32 v249, v249, v90, v91
	s_waitcnt lgkmcnt(4)
	v_mfma_f32_32x32x16_bf16 v[64:79], v[234:237], v[132:135], v[64:79]
	ds_read_b64_tr_b16 v[218:219], v185 offset:4096
	ds_read_b64_tr_b16 v[220:221], v185 offset:6144
	v_max3_f32 v249, v249, v92, v93
	v_max3_f32 v249, v249, v94, v95
	s_waitcnt lgkmcnt(5)
	v_mfma_f32_32x32x16_bf16 v[64:79], v[238:241], v[136:139], v[64:79]
	ds_read_b64_tr_b16 v[222:223], v185 offset:8192
	ds_read_b64_tr_b16 v[224:225], v185 offset:10240
	s_waitcnt lgkmcnt(6)
	v_mfma_f32_32x32x16_bf16 v[64:79], v[242:245], v[140:143], v[64:79]
	ds_read_b64_tr_b16 v[226:227], v185 offset:12288
	ds_read_b64_tr_b16 v[228:229], v185 offset:14336
	s_waitcnt lgkmcnt(6)
	v_mfma_f32_32x32x16_bf16 v[0:15], v[144:147], v[214:217], v[0:15]
	ds_read_b64_tr_b16 v[214:215], v185 offset:512
	ds_read_b64_tr_b16 v[216:217], v185 offset:2560
	s_waitcnt lgkmcnt(6)
	v_mfma_f32_32x32x16_bf16 v[0:15], v[148:151], v[218:221], v[0:15]
	ds_read_b64_tr_b16 v[218:219], v185 offset:4608
	ds_read_b64_tr_b16 v[220:221], v185 offset:6656
	s_waitcnt lgkmcnt(6)
	v_mfma_f32_32x32x16_bf16 v[0:15], v[152:155], v[222:225], v[0:15]
	ds_read_b64_tr_b16 v[222:223], v185 offset:8704
	ds_read_b64_tr_b16 v[224:225], v185 offset:10752
	s_waitcnt lgkmcnt(6)
	v_mfma_f32_32x32x16_bf16 v[0:15], v[156:159], v[226:229], v[0:15]
	ds_read_b64_tr_b16 v[226:227], v185 offset:12800
	ds_read_b64_tr_b16 v[228:229], v185 offset:14848
	s_waitcnt lgkmcnt(6)
	v_mfma_f32_32x32x16_bf16 v[48:63], v[144:147], v[214:217], v[48:63]
	ds_read_b64_tr_b16 v[214:215], v185 offset:1024
	ds_read_b64_tr_b16 v[216:217], v185 offset:3072
	v_max3_f32 v249, v249, v64, v65
	v_max3_f32 v249, v249, v66, v67
	v_max3_f32 v249, v249, v68, v69
	v_max3_f32 v249, v249, v70, v71
	v_max3_f32 v249, v249, v72, v73
	v_max3_f32 v249, v249, v74, v75
	v_max3_f32 v249, v249, v76, v77
	v_max3_f32 v249, v249, v78, v79
	s_waitcnt lgkmcnt(6)
	v_mfma_f32_32x32x16_bf16 v[48:63], v[148:151], v[218:221], v[48:63]
	ds_read_b64_tr_b16 v[218:219], v185 offset:5120
	ds_read_b64_tr_b16 v[220:221], v185 offset:7168
	v_mov_b32_e32 v250, v249
	s_nop 1
	v_permlane32_swap_b32_e32 v249, v250
	v_max_f32_e32 v249, v249, v250
	v_sub_f32_e32 v250, v249, v208
	v_cmp_ge_f32_e32 vcc, s40, v250
	v_max_f32_e32 v249, v208, v249
	v_sub_f32_e32 v250, v208, v249
	s_waitcnt lgkmcnt(6)
	v_mfma_f32_32x32x16_bf16 v[48:63], v[152:155], v[222:225], v[48:63]
	ds_read_b64_tr_b16 v[222:223], v185 offset:9216
	ds_read_b64_tr_b16 v[224:225], v185 offset:11264
	v_mul_f32_e32 v250, 0x3dd53b94, v250
	v_exp_f32_e32 v250, v250
	s_cmp_eq_u64 vcc, exec
	s_cselect_b64 s[10:11], -1, 0
	v_cndmask_b32_e64 v207, v250, 1.0, s[10:11]
	v_cndmask_b32_e64 v208, v249, v208, s[10:11]
	v_mul_f32_e32 v251, 0xbdd53b94, v208
	v_fmamk_f32 v80, v80, 0x3dd53b94, v251
	s_waitcnt lgkmcnt(6)
	v_mfma_f32_32x32x16_bf16 v[48:63], v[156:159], v[226:229], v[48:63]
	ds_read_b64_tr_b16 v[226:227], v185 offset:13312
	ds_read_b64_tr_b16 v[228:229], v185 offset:15360
	v_fmamk_f32 v81, v81, 0x3dd53b94, v251
	v_fmamk_f32 v82, v82, 0x3dd53b94, v251
	v_fmamk_f32 v83, v83, 0x3dd53b94, v251
	v_fmamk_f32 v84, v84, 0x3dd53b94, v251
	v_fmamk_f32 v85, v85, 0x3dd53b94, v251
	v_fmamk_f32 v86, v86, 0x3dd53b94, v251
	v_fmamk_f32 v87, v87, 0x3dd53b94, v251
	s_waitcnt lgkmcnt(6)
	v_mfma_f32_32x32x16_bf16 v[32:47], v[144:147], v[214:217], v[32:47]
	ds_read_b64_tr_b16 v[214:215], v185 offset:1536
	ds_read_b64_tr_b16 v[216:217], v185 offset:3584
	v_fmamk_f32 v88, v88, 0x3dd53b94, v251
	v_fmamk_f32 v89, v89, 0x3dd53b94, v251
	v_fmamk_f32 v90, v90, 0x3dd53b94, v251
	v_fmamk_f32 v91, v91, 0x3dd53b94, v251
	v_fmamk_f32 v92, v92, 0x3dd53b94, v251
	v_fmamk_f32 v93, v93, 0x3dd53b94, v251
	v_fmamk_f32 v94, v94, 0x3dd53b94, v251
	s_waitcnt lgkmcnt(6)
	v_mfma_f32_32x32x16_bf16 v[32:47], v[148:151], v[218:221], v[32:47]
	ds_read_b64_tr_b16 v[218:219], v185 offset:5632
	ds_read_b64_tr_b16 v[220:221], v185 offset:7680
	v_fmamk_f32 v95, v95, 0x3dd53b94, v251
	v_exp_f32_e32 v80, v80
	v_fmamk_f32 v64, v64, 0x3dd53b94, v251
	v_exp_f32_e32 v81, v81
	v_fmamk_f32 v65, v65, 0x3dd53b94, v251
	v_add_f32_e32 v212, 0, v80
	v_exp_f32_e32 v82, v82
	s_waitcnt lgkmcnt(6)
	v_mfma_f32_32x32x16_bf16 v[32:47], v[152:155], v[222:225], v[32:47]
	ds_read_b64_tr_b16 v[222:223], v185 offset:9728
	ds_read_b64_tr_b16 v[224:225], v185 offset:11776
	v_fmamk_f32 v66, v66, 0x3dd53b94, v251
	v_add_f32_e32 v212, v81, v212
	v_exp_f32_e32 v83, v83
	v_fmamk_f32 v67, v67, 0x3dd53b94, v251
	v_add_f32_e32 v212, v82, v212
	v_exp_f32_e32 v84, v84
	v_fmamk_f32 v68, v68, 0x3dd53b94, v251
	s_waitcnt lgkmcnt(6)
	v_mfma_f32_32x32x16_bf16 v[32:47], v[156:159], v[226:229], v[32:47]
	ds_read_b64_tr_b16 v[226:227], v185 offset:13824
	ds_read_b64_tr_b16 v[228:229], v185 offset:15872
	v_add_f32_e32 v212, v83, v212
	v_exp_f32_e32 v85, v85
	v_fmamk_f32 v69, v69, 0x3dd53b94, v251
	v_add_f32_e32 v212, v84, v212
	v_exp_f32_e32 v86, v86
	v_fmamk_f32 v70, v70, 0x3dd53b94, v251
	v_add_f32_e32 v212, v85, v212
	s_waitcnt lgkmcnt(6)
	v_mfma_f32_32x32x16_bf16 v[16:31], v[144:147], v[214:217], v[16:31]
	v_exp_f32_e32 v87, v87
	v_fmamk_f32 v71, v71, 0x3dd53b94, v251
	v_add_f32_e32 v212, v86, v212
	v_exp_f32_e32 v88, v88
	v_fmamk_f32 v72, v72, 0x3dd53b94, v251
	v_add_f32_e32 v212, v87, v212
	v_exp_f32_e32 v89, v89
	s_waitcnt lgkmcnt(4)
	v_mfma_f32_32x32x16_bf16 v[16:31], v[148:151], v[218:221], v[16:31]
	v_fmamk_f32 v73, v73, 0x3dd53b94, v251
	v_add_f32_e32 v212, v88, v212
	v_exp_f32_e32 v90, v90
	v_fmamk_f32 v74, v74, 0x3dd53b94, v251
	v_add_f32_e32 v212, v89, v212
	v_exp_f32_e32 v91, v91
	v_fmamk_f32 v75, v75, 0x3dd53b94, v251
	s_waitcnt lgkmcnt(2)
	v_mfma_f32_32x32x16_bf16 v[16:31], v[152:155], v[222:225], v[16:31]
	v_add_f32_e32 v212, v90, v212
	v_exp_f32_e32 v92, v92
	v_fmamk_f32 v76, v76, 0x3dd53b94, v251
	v_add_f32_e32 v212, v91, v212
	v_exp_f32_e32 v93, v93
	v_fmamk_f32 v77, v77, 0x3dd53b94, v251
	v_add_f32_e32 v212, v92, v212
	s_waitcnt lgkmcnt(0)
	v_mfma_f32_32x32x16_bf16 v[16:31], v[156:159], v[226:229], v[16:31]
	v_exp_f32_e32 v94, v94
	v_fmamk_f32 v78, v78, 0x3dd53b94, v251
	v_add_f32_e32 v212, v93, v212
	v_exp_f32_e32 v95, v95
	v_fmamk_f32 v79, v79, 0x3dd53b94, v251
	v_add_f32_e32 v212, v94, v212
	v_add_f32_e32 v212, v95, v212
	v_cvt_pk_bf16_f32 v144, v80, v81
	v_cvt_pk_bf16_f32 v145, v82, v83
	v_cvt_pk_bf16_f32 v146, v84, v85
	v_cvt_pk_bf16_f32 v147, v86, v87
	v_cvt_pk_bf16_f32 v148, v88, v89
	v_cvt_pk_bf16_f32 v149, v90, v91
	v_cvt_pk_bf16_f32 v150, v92, v93
	v_cvt_pk_bf16_f32 v151, v94, v95
	v_permlane32_swap_b32_e32 v144, v146
	v_permlane32_swap_b32_e32 v145, v147
	v_permlane32_swap_b32_e32 v148, v150
	v_permlane32_swap_b32_e32 v149, v151
	v_cmp_gt_f32_e32 vcc, 1.0, v207
	s_cbranch_vccz .Lmla_noresc_o
	s_and_saveexec_b64 s[0:1], s[8:9]
	ds_write_b32 v182, v207 offset:128
	s_or_b64 exec, exec, s[0:1]
	s_waitcnt lgkmcnt(0)
	v_add_u32_e32 v253, s50, v181
	ds_read_b128 v[92:95], v253 offset:224
	ds_read_b128 v[88:91], v253 offset:192
	ds_read_b128 v[84:87], v253 offset:160
	ds_read_b128 v[80:83], v253 offset:128
	s_waitcnt lgkmcnt(3)
	v_pk_mul_f32 v[12:13], v[12:13], v[92:93]
	v_pk_mul_f32 v[14:15], v[14:15], v[94:95]
	v_pk_mul_f32 v[60:61], v[60:61], v[92:93]
	v_pk_mul_f32 v[62:63], v[62:63], v[94:95]
	v_pk_mul_f32 v[44:45], v[44:45], v[92:93]
	v_pk_mul_f32 v[46:47], v[46:47], v[94:95]
	v_pk_mul_f32 v[28:29], v[28:29], v[92:93]
	v_pk_mul_f32 v[30:31], v[30:31], v[94:95]
	s_waitcnt lgkmcnt(2)
	v_pk_mul_f32 v[8:9], v[8:9], v[88:89]
	v_pk_mul_f32 v[10:11], v[10:11], v[90:91]
	v_pk_mul_f32 v[56:57], v[56:57], v[88:89]
	v_pk_mul_f32 v[58:59], v[58:59], v[90:91]
	v_pk_mul_f32 v[40:41], v[40:41], v[88:89]
	v_pk_mul_f32 v[42:43], v[42:43], v[90:91]
	v_pk_mul_f32 v[24:25], v[24:25], v[88:89]
	v_pk_mul_f32 v[26:27], v[26:27], v[90:91]
	s_waitcnt lgkmcnt(1)
	v_pk_mul_f32 v[4:5], v[4:5], v[84:85]
	v_pk_mul_f32 v[6:7], v[6:7], v[86:87]
	v_pk_mul_f32 v[52:53], v[52:53], v[84:85]
	v_pk_mul_f32 v[54:55], v[54:55], v[86:87]
	v_pk_mul_f32 v[36:37], v[36:37], v[84:85]
	v_pk_mul_f32 v[38:39], v[38:39], v[86:87]
	v_pk_mul_f32 v[20:21], v[20:21], v[84:85]
	v_pk_mul_f32 v[22:23], v[22:23], v[86:87]
	s_waitcnt lgkmcnt(0)
	v_pk_mul_f32 v[0:1], v[0:1], v[80:81]
	v_pk_mul_f32 v[2:3], v[2:3], v[82:83]
	v_pk_mul_f32 v[48:49], v[48:49], v[80:81]
	v_pk_mul_f32 v[50:51], v[50:51], v[82:83]
	v_pk_mul_f32 v[32:33], v[32:33], v[80:81]
	v_pk_mul_f32 v[34:35], v[34:35], v[82:83]
	v_pk_mul_f32 v[16:17], v[16:17], v[80:81]
	v_pk_mul_f32 v[18:19], v[18:19], v[82:83]
.Lmla_noresc_o:
	s_add_i32 s58, s58, 1
	s_waitcnt vmcnt(0) lgkmcnt(0)
	s_barrier
	ds_read_b128 v[230:233], v193 offset:32768
	ds_read_b128 v[234:237], v186 offset:32768
	ds_read_b128 v[238:241], v187 offset:32768
	ds_read_b128 v[242:245], v188 offset:32768
	s_cmp_lt_u32 s58, s18
	s_cselect_b32 s0, 0, s18
	s_cselect_b32 s1, s6, s13
	s_lshl_b32 s0, s0, 6
	s_sub_i32 s0, s1, s0
	s_add_i32 s0, s51, s0
	s_add_i32 s0, s0, 64
	s_ashr_i32 s1, s0, 31
	s_lshl_b64 s[10:11], s[0:1], 12
	s_add_u32 s16, s20, s10
	s_addc_u32 s17, s21, s11
	v_exp_f32_e32 v64, v64
	v_exp_f32_e32 v65, v65
	v_add_f32_e32 v212, v64, v212
	v_exp_f32_e32 v66, v66
	v_add_f32_e32 v212, v65, v212
	v_exp_f32_e32 v67, v67
	s_waitcnt lgkmcnt(3)
	v_mfma_f32_32x32x16_bf16 v[80:95], v[230:233], v[124:127], 0
	ds_read_b128 v[230:233], v189 offset:32768
	s_mov_b32 m0, s22
	v_lshl_add_u64 v[254:255], v[164:165], 1, s[100:101]
	global_load_lds_dwordx4 v[254:255], off
	v_add_f32_e32 v212, v66, v212
	v_exp_f32_e32 v68, v68
	v_add_f32_e32 v212, v67, v212
	v_exp_f32_e32 v69, v69
	s_waitcnt lgkmcnt(3)
	v_mfma_f32_32x32x16_bf16 v[80:95], v[234:237], v[120:123], v[80:95]
	ds_read_b128 v[234:237], v190 offset:32768
	v_add_f32_e32 v212, v68, v212
	v_exp_f32_e32 v70, v70
	v_add_f32_e32 v212, v69, v212
	v_exp_f32_e32 v71, v71
	s_waitcnt lgkmcnt(3)
	v_mfma_f32_32x32x16_bf16 v[80:95], v[238:241], v[116:119], v[80:95]
	ds_read_b128 v[238:241], v191 offset:32768
	s_mov_b32 m0, s31
	v_lshl_add_u64 v[254:255], v[166:167], 1, s[100:101]
	global_load_lds_dwordx4 v[254:255], off
	v_add_f32_e32 v212, v70, v212
	v_exp_f32_e32 v72, v72
	v_add_f32_e32 v212, v71, v212
	v_exp_f32_e32 v73, v73
	s_waitcnt lgkmcnt(3)
	v_mfma_f32_32x32x16_bf16 v[80:95], v[242:245], v[112:115], v[80:95]
	ds_read_b128 v[242:245], v192 offset:32768
	v_add_f32_e32 v212, v72, v212
	v_exp_f32_e32 v74, v74
	v_add_f32_e32 v212, v73, v212
	v_exp_f32_e32 v75, v75
	s_waitcnt lgkmcnt(3)
	v_mfma_f32_32x32x16_bf16 v[80:95], v[230:233], v[108:111], v[80:95]
	ds_read_b128 v[230:233], v203 offset:49152
	s_mov_b32 m0, s44
	v_lshl_add_u64 v[254:255], v[160:161], 1, s[16:17]
	global_load_lds_dwordx4 v[254:255], off
	v_add_f32_e32 v212, v74, v212
	v_exp_f32_e32 v76, v76
	v_add_f32_e32 v212, v75, v212
	v_exp_f32_e32 v77, v77
	s_waitcnt lgkmcnt(3)
	v_mfma_f32_32x32x16_bf16 v[80:95], v[234:237], v[104:107], v[80:95]
	ds_read_b128 v[234:237], v204 offset:49152
	v_add_f32_e32 v212, v76, v212
	v_exp_f32_e32 v78, v78
	v_add_f32_e32 v212, v77, v212
	v_exp_f32_e32 v79, v79
	s_waitcnt lgkmcnt(3)
	v_mfma_f32_32x32x16_bf16 v[80:95], v[238:241], v[100:103], v[80:95]
	ds_read_b128 v[238:241], v205 offset:49152
	v_add_f32_e32 v212, v78, v212
	v_add_f32_e32 v212, v79, v212
	v_mov_b32_e32 v213, v212
	s_waitcnt lgkmcnt(3)
	v_mfma_f32_32x32x16_bf16 v[80:95], v[242:245], v[96:99], v[80:95]
	ds_read_b128 v[242:245], v206 offset:49152
	s_mov_b32 m0, s45
	v_lshl_add_u64 v[254:255], v[162:163], 1, s[16:17]
	global_load_lds_dwordx4 v[254:255], off
	v_cvt_pk_bf16_f32 v152, v64, v65
	v_cvt_pk_bf16_f32 v153, v66, v67
	v_cvt_pk_bf16_f32 v154, v68, v69
	s_waitcnt lgkmcnt(3)
	v_mfma_f32_32x32x16_bf16 v[80:95], v[230:233], v[128:131], v[80:95]
	ds_read_b128 v[230:233], v193 offset:40960
	v_cvt_pk_bf16_f32 v155, v70, v71
	v_cvt_pk_bf16_f32 v156, v72, v73
	v_cvt_pk_bf16_f32 v157, v74, v75
	s_waitcnt lgkmcnt(3)
	v_mfma_f32_32x32x16_bf16 v[80:95], v[234:237], v[132:135], v[80:95]
	ds_read_b128 v[234:237], v186 offset:40960
	v_cvt_pk_bf16_f32 v158, v76, v77
	v_cvt_pk_bf16_f32 v159, v78, v79
	v_permlane32_swap_b32_e32 v212, v213
	s_waitcnt lgkmcnt(3)
	v_mfma_f32_32x32x16_bf16 v[80:95], v[238:241], v[136:139], v[80:95]
	ds_read_b128 v[238:241], v187 offset:40960
	s_mov_b32 m0, s49
	v_mad_i64_i32 v[254:255], s[0:1], s0, v180, v[168:169]
	global_load_lds_dwordx4 v[254:255], off
	s_add_u32 s100, s16, 0x100
	s_addc_u32 s101, s17, 0
	v_add_f32_e32 v252, v212, v213
	v_fma_f32 v183, v207, v183, v252
	v_permlane32_swap_b32_e32 v152, v154
	s_waitcnt lgkmcnt(3)
	v_mfma_f32_32x32x16_bf16 v[80:95], v[242:245], v[140:143], v[80:95]
	ds_read_b128 v[242:245], v188 offset:40960
	v_permlane32_swap_b32_e32 v153, v155
	v_permlane32_swap_b32_e32 v156, v158
	v_permlane32_swap_b32_e32 v157, v159
	s_waitcnt lgkmcnt(3)
	v_mfma_f32_32x32x16_bf16 v[64:79], v[230:233], v[124:127], 0
	ds_read_b128 v[230:233], v189 offset:40960
	s_waitcnt lgkmcnt(3)
	v_mfma_f32_32x32x16_bf16 v[64:79], v[234:237], v[120:123], v[64:79]
	ds_read_b128 v[234:237], v190 offset:40960
	s_waitcnt lgkmcnt(3)
	v_mfma_f32_32x32x16_bf16 v[64:79], v[238:241], v[116:119], v[64:79]
	ds_read_b128 v[238:241], v191 offset:40960
	s_waitcnt lgkmcnt(3)
	v_mfma_f32_32x32x16_bf16 v[64:79], v[242:245], v[112:115], v[64:79]
	ds_read_b128 v[242:245], v192 offset:40960
	s_waitcnt lgkmcnt(3)
	v_mfma_f32_32x32x16_bf16 v[64:79], v[230:233], v[108:111], v[64:79]
	ds_read_b128 v[230:233], v203 offset:53248
	s_waitcnt lgkmcnt(3)
	v_mfma_f32_32x32x16_bf16 v[64:79], v[234:237], v[104:107], v[64:79]
	ds_read_b128 v[234:237], v204 offset:53248
	s_waitcnt lgkmcnt(3)
	v_mfma_f32_32x32x16_bf16 v[64:79], v[238:241], v[100:103], v[64:79]
	ds_read_b128 v[238:241], v205 offset:53248
	v_max_f32_e32 v249, v80, v81
	v_max3_f32 v249, v249, v82, v83
	s_waitcnt lgkmcnt(3)
	v_mfma_f32_32x32x16_bf16 v[64:79], v[242:245], v[96:99], v[64:79]
	ds_read_b128 v[242:245], v206 offset:53248
	v_max3_f32 v249, v249, v84, v85
	v_max3_f32 v249, v249, v86, v87
	s_waitcnt lgkmcnt(3)
	v_mfma_f32_32x32x16_bf16 v[64:79], v[230:233], v[128:131], v[64:79]
	ds_read_b64_tr_b16 v[214:215], v184
	ds_read_b64_tr_b16 v[216:217], v184 offset:2048
	v_max3_f32 v249, v249, v88, v89
	v_max3_f32 v249, v249, v90, v91
	s_waitcnt lgkmcnt(4)
	v_mfma_f32_32x32x16_bf16 v[64:79], v[234:237], v[132:135], v[64:79]
	ds_read_b64_tr_b16 v[218:219], v184 offset:4096
	ds_read_b64_tr_b16 v[220:221], v184 offset:6144
	v_max3_f32 v249, v249, v92, v93
	v_max3_f32 v249, v249, v94, v95
	s_waitcnt lgkmcnt(5)
	v_mfma_f32_32x32x16_bf16 v[64:79], v[238:241], v[136:139], v[64:79]
	ds_read_b64_tr_b16 v[222:223], v184 offset:8192
	ds_read_b64_tr_b16 v[224:225], v184 offset:10240
	s_waitcnt lgkmcnt(6)
	v_mfma_f32_32x32x16_bf16 v[64:79], v[242:245], v[140:143], v[64:79]
	ds_read_b64_tr_b16 v[226:227], v184 offset:12288
	ds_read_b64_tr_b16 v[228:229], v184 offset:14336
	s_waitcnt lgkmcnt(6)
	v_mfma_f32_32x32x16_bf16 v[0:15], v[144:147], v[214:217], v[0:15]
	ds_read_b64_tr_b16 v[214:215], v184 offset:512
	ds_read_b64_tr_b16 v[216:217], v184 offset:2560
	s_waitcnt lgkmcnt(6)
	v_mfma_f32_32x32x16_bf16 v[0:15], v[148:151], v[218:221], v[0:15]
	ds_read_b64_tr_b16 v[218:219], v184 offset:4608
	ds_read_b64_tr_b16 v[220:221], v184 offset:6656
	s_waitcnt lgkmcnt(6)
	v_mfma_f32_32x32x16_bf16 v[0:15], v[152:155], v[222:225], v[0:15]
	ds_read_b64_tr_b16 v[222:223], v184 offset:8704
	ds_read_b64_tr_b16 v[224:225], v184 offset:10752
	s_waitcnt lgkmcnt(6)
	v_mfma_f32_32x32x16_bf16 v[0:15], v[156:159], v[226:229], v[0:15]
	ds_read_b64_tr_b16 v[226:227], v184 offset:12800
	ds_read_b64_tr_b16 v[228:229], v184 offset:14848
	s_waitcnt lgkmcnt(6)
	v_mfma_f32_32x32x16_bf16 v[48:63], v[144:147], v[214:217], v[48:63]
	ds_read_b64_tr_b16 v[214:215], v184 offset:1024
	ds_read_b64_tr_b16 v[216:217], v184 offset:3072
	v_max3_f32 v249, v249, v64, v65
	v_max3_f32 v249, v249, v66, v67
	v_max3_f32 v249, v249, v68, v69
	v_max3_f32 v249, v249, v70, v71
	v_max3_f32 v249, v249, v72, v73
	v_max3_f32 v249, v249, v74, v75
	v_max3_f32 v249, v249, v76, v77
	v_max3_f32 v249, v249, v78, v79
	s_waitcnt lgkmcnt(6)
	v_mfma_f32_32x32x16_bf16 v[48:63], v[148:151], v[218:221], v[48:63]
	ds_read_b64_tr_b16 v[218:219], v184 offset:5120
	ds_read_b64_tr_b16 v[220:221], v184 offset:7168
	v_mov_b32_e32 v250, v249
	s_nop 1
	v_permlane32_swap_b32_e32 v249, v250
	v_max_f32_e32 v249, v249, v250
	v_sub_f32_e32 v250, v249, v208
	v_cmp_ge_f32_e32 vcc, s40, v250
	v_max_f32_e32 v249, v208, v249
	v_sub_f32_e32 v250, v208, v249
	s_waitcnt lgkmcnt(6)
	v_mfma_f32_32x32x16_bf16 v[48:63], v[152:155], v[222:225], v[48:63]
	ds_read_b64_tr_b16 v[222:223], v184 offset:9216
	ds_read_b64_tr_b16 v[224:225], v184 offset:11264
	v_mul_f32_e32 v250, 0x3dd53b94, v250
	v_exp_f32_e32 v250, v250
	s_cmp_eq_u64 vcc, exec
	s_cselect_b64 s[10:11], -1, 0
	v_cndmask_b32_e64 v207, v250, 1.0, s[10:11]
	v_cndmask_b32_e64 v208, v249, v208, s[10:11]
	v_mul_f32_e32 v251, 0xbdd53b94, v208
	v_fmamk_f32 v80, v80, 0x3dd53b94, v251
	s_waitcnt lgkmcnt(6)
	v_mfma_f32_32x32x16_bf16 v[48:63], v[156:159], v[226:229], v[48:63]
	ds_read_b64_tr_b16 v[226:227], v184 offset:13312
	ds_read_b64_tr_b16 v[228:229], v184 offset:15360
	v_fmamk_f32 v81, v81, 0x3dd53b94, v251
	v_fmamk_f32 v82, v82, 0x3dd53b94, v251
	v_fmamk_f32 v83, v83, 0x3dd53b94, v251
	v_fmamk_f32 v84, v84, 0x3dd53b94, v251
	v_fmamk_f32 v85, v85, 0x3dd53b94, v251
	v_fmamk_f32 v86, v86, 0x3dd53b94, v251
	v_fmamk_f32 v87, v87, 0x3dd53b94, v251
	s_waitcnt lgkmcnt(6)
	v_mfma_f32_32x32x16_bf16 v[32:47], v[144:147], v[214:217], v[32:47]
	ds_read_b64_tr_b16 v[214:215], v184 offset:1536
	ds_read_b64_tr_b16 v[216:217], v184 offset:3584
	v_fmamk_f32 v88, v88, 0x3dd53b94, v251
	v_fmamk_f32 v89, v89, 0x3dd53b94, v251
	v_fmamk_f32 v90, v90, 0x3dd53b94, v251
	v_fmamk_f32 v91, v91, 0x3dd53b94, v251
	v_fmamk_f32 v92, v92, 0x3dd53b94, v251
	v_fmamk_f32 v93, v93, 0x3dd53b94, v251
	v_fmamk_f32 v94, v94, 0x3dd53b94, v251
	s_waitcnt lgkmcnt(6)
	v_mfma_f32_32x32x16_bf16 v[32:47], v[148:151], v[218:221], v[32:47]
	ds_read_b64_tr_b16 v[218:219], v184 offset:5632
	ds_read_b64_tr_b16 v[220:221], v184 offset:7680
	v_fmamk_f32 v95, v95, 0x3dd53b94, v251
	v_exp_f32_e32 v80, v80
	v_fmamk_f32 v64, v64, 0x3dd53b94, v251
	v_exp_f32_e32 v81, v81
	v_fmamk_f32 v65, v65, 0x3dd53b94, v251
	v_add_f32_e32 v212, 0, v80
	v_exp_f32_e32 v82, v82
	s_waitcnt lgkmcnt(6)
	v_mfma_f32_32x32x16_bf16 v[32:47], v[152:155], v[222:225], v[32:47]
	ds_read_b64_tr_b16 v[222:223], v184 offset:9728
	ds_read_b64_tr_b16 v[224:225], v184 offset:11776
	v_fmamk_f32 v66, v66, 0x3dd53b94, v251
	v_add_f32_e32 v212, v81, v212
	v_exp_f32_e32 v83, v83
	v_fmamk_f32 v67, v67, 0x3dd53b94, v251
	v_add_f32_e32 v212, v82, v212
	v_exp_f32_e32 v84, v84
	v_fmamk_f32 v68, v68, 0x3dd53b94, v251
	s_waitcnt lgkmcnt(6)
	v_mfma_f32_32x32x16_bf16 v[32:47], v[156:159], v[226:229], v[32:47]
	ds_read_b64_tr_b16 v[226:227], v184 offset:13824
	ds_read_b64_tr_b16 v[228:229], v184 offset:15872
	v_add_f32_e32 v212, v83, v212
	v_exp_f32_e32 v85, v85
	v_fmamk_f32 v69, v69, 0x3dd53b94, v251
	v_add_f32_e32 v212, v84, v212
	v_exp_f32_e32 v86, v86
	v_fmamk_f32 v70, v70, 0x3dd53b94, v251
	v_add_f32_e32 v212, v85, v212
	s_waitcnt lgkmcnt(6)
	v_mfma_f32_32x32x16_bf16 v[16:31], v[144:147], v[214:217], v[16:31]
	v_exp_f32_e32 v87, v87
	v_fmamk_f32 v71, v71, 0x3dd53b94, v251
	v_add_f32_e32 v212, v86, v212
	v_exp_f32_e32 v88, v88
	v_fmamk_f32 v72, v72, 0x3dd53b94, v251
	v_add_f32_e32 v212, v87, v212
	v_exp_f32_e32 v89, v89
	s_waitcnt lgkmcnt(4)
	v_mfma_f32_32x32x16_bf16 v[16:31], v[148:151], v[218:221], v[16:31]
	v_fmamk_f32 v73, v73, 0x3dd53b94, v251
	v_add_f32_e32 v212, v88, v212
	v_exp_f32_e32 v90, v90
	v_fmamk_f32 v74, v74, 0x3dd53b94, v251
	v_add_f32_e32 v212, v89, v212
	v_exp_f32_e32 v91, v91
	v_fmamk_f32 v75, v75, 0x3dd53b94, v251
	s_waitcnt lgkmcnt(2)
	v_mfma_f32_32x32x16_bf16 v[16:31], v[152:155], v[222:225], v[16:31]
	v_add_f32_e32 v212, v90, v212
	v_exp_f32_e32 v92, v92
	v_fmamk_f32 v76, v76, 0x3dd53b94, v251
	v_add_f32_e32 v212, v91, v212
	v_exp_f32_e32 v93, v93
	v_fmamk_f32 v77, v77, 0x3dd53b94, v251
	v_add_f32_e32 v212, v92, v212
	s_waitcnt lgkmcnt(0)
	v_mfma_f32_32x32x16_bf16 v[16:31], v[156:159], v[226:229], v[16:31]
	v_exp_f32_e32 v94, v94
	v_fmamk_f32 v78, v78, 0x3dd53b94, v251
	v_add_f32_e32 v212, v93, v212
	v_exp_f32_e32 v95, v95
	v_fmamk_f32 v79, v79, 0x3dd53b94, v251
	v_add_f32_e32 v212, v94, v212
	v_add_f32_e32 v212, v95, v212
	v_cvt_pk_bf16_f32 v144, v80, v81
	v_cvt_pk_bf16_f32 v145, v82, v83
	v_cvt_pk_bf16_f32 v146, v84, v85
	v_cvt_pk_bf16_f32 v147, v86, v87
	v_cvt_pk_bf16_f32 v148, v88, v89
	v_cvt_pk_bf16_f32 v149, v90, v91
	v_cvt_pk_bf16_f32 v150, v92, v93
	v_cvt_pk_bf16_f32 v151, v94, v95
	v_permlane32_swap_b32_e32 v144, v146
	v_permlane32_swap_b32_e32 v145, v147
	v_permlane32_swap_b32_e32 v148, v150
	v_permlane32_swap_b32_e32 v149, v151
	v_cmp_gt_f32_e32 vcc, 1.0, v207
	s_cbranch_vccz .Lmla_noresc_e
	s_and_saveexec_b64 s[0:1], s[8:9]
	ds_write_b32 v182, v207 offset:128
	s_or_b64 exec, exec, s[0:1]
	s_waitcnt lgkmcnt(0)
	v_add_u32_e32 v253, s50, v181
	ds_read_b128 v[92:95], v253 offset:224
	ds_read_b128 v[88:91], v253 offset:192
	ds_read_b128 v[84:87], v253 offset:160
	ds_read_b128 v[80:83], v253 offset:128
	s_waitcnt lgkmcnt(3)
	v_pk_mul_f32 v[12:13], v[12:13], v[92:93]
	v_pk_mul_f32 v[14:15], v[14:15], v[94:95]
	v_pk_mul_f32 v[60:61], v[60:61], v[92:93]
	v_pk_mul_f32 v[62:63], v[62:63], v[94:95]
	v_pk_mul_f32 v[44:45], v[44:45], v[92:93]
	v_pk_mul_f32 v[46:47], v[46:47], v[94:95]
	v_pk_mul_f32 v[28:29], v[28:29], v[92:93]
	v_pk_mul_f32 v[30:31], v[30:31], v[94:95]
	s_waitcnt lgkmcnt(2)
	v_pk_mul_f32 v[8:9], v[8:9], v[88:89]
	v_pk_mul_f32 v[10:11], v[10:11], v[90:91]
	v_pk_mul_f32 v[56:57], v[56:57], v[88:89]
	v_pk_mul_f32 v[58:59], v[58:59], v[90:91]
	v_pk_mul_f32 v[40:41], v[40:41], v[88:89]
	v_pk_mul_f32 v[42:43], v[42:43], v[90:91]
	v_pk_mul_f32 v[24:25], v[24:25], v[88:89]
	v_pk_mul_f32 v[26:27], v[26:27], v[90:91]
	s_waitcnt lgkmcnt(1)
	v_pk_mul_f32 v[4:5], v[4:5], v[84:85]
	v_pk_mul_f32 v[6:7], v[6:7], v[86:87]
	v_pk_mul_f32 v[52:53], v[52:53], v[84:85]
	v_pk_mul_f32 v[54:55], v[54:55], v[86:87]
	v_pk_mul_f32 v[36:37], v[36:37], v[84:85]
	v_pk_mul_f32 v[38:39], v[38:39], v[86:87]
	v_pk_mul_f32 v[20:21], v[20:21], v[84:85]
	v_pk_mul_f32 v[22:23], v[22:23], v[86:87]
	s_waitcnt lgkmcnt(0)
	v_pk_mul_f32 v[0:1], v[0:1], v[80:81]
	v_pk_mul_f32 v[2:3], v[2:3], v[82:83]
	v_pk_mul_f32 v[48:49], v[48:49], v[80:81]
	v_pk_mul_f32 v[50:51], v[50:51], v[82:83]
	v_pk_mul_f32 v[32:33], v[32:33], v[80:81]
	v_pk_mul_f32 v[34:35], v[34:35], v[82:83]
	v_pk_mul_f32 v[16:17], v[16:17], v[80:81]
	v_pk_mul_f32 v[18:19], v[18:19], v[82:83]
.Lmla_noresc_e:
	s_add_i32 s58, s58, 1
	s_addk_i32 s51, 0x80
	s_waitcnt vmcnt(0) lgkmcnt(0)
	s_barrier
	s_cmp_ge_u32 s58, s19
	s_cbranch_scc0 .Lmla_loop
	ds_read_b128 v[230:233], v193 offset:57344
	ds_read_b128 v[234:237], v186 offset:57344
	ds_read_b128 v[238:241], v187 offset:57344
	ds_read_b128 v[242:245], v188 offset:57344
	v_exp_f32_e32 v64, v64
	v_exp_f32_e32 v65, v65
	v_add_f32_e32 v212, v64, v212
	v_exp_f32_e32 v66, v66
	v_add_f32_e32 v212, v65, v212
	v_exp_f32_e32 v67, v67
	s_waitcnt lgkmcnt(3)
	v_mfma_f32_32x32x16_bf16 v[80:95], v[230:233], v[124:127], 0
	ds_read_b128 v[230:233], v189 offset:57344
	s_mov_b32 m0, s54
	v_lshl_add_u64 v[254:255], v[164:165], 1, s[100:101]
	global_load_lds_dwordx4 v[254:255], off
	v_add_f32_e32 v212, v66, v212
	v_exp_f32_e32 v68, v68
	v_add_f32_e32 v212, v67, v212
	v_exp_f32_e32 v69, v69
	s_waitcnt lgkmcnt(3)
	v_mfma_f32_32x32x16_bf16 v[80:95], v[234:237], v[120:123], v[80:95]
	ds_read_b128 v[234:237], v190 offset:57344
	v_add_f32_e32 v212, v68, v212
	v_exp_f32_e32 v70, v70
	v_add_f32_e32 v212, v69, v212
	v_exp_f32_e32 v71, v71
	s_waitcnt lgkmcnt(3)
	v_mfma_f32_32x32x16_bf16 v[80:95], v[238:241], v[116:119], v[80:95]
	ds_read_b128 v[238:241], v191 offset:57344
	s_mov_b32 m0, s55
	v_lshl_add_u64 v[254:255], v[166:167], 1, s[100:101]
	global_load_lds_dwordx4 v[254:255], off
	v_add_f32_e32 v212, v70, v212
	v_exp_f32_e32 v72, v72
	v_add_f32_e32 v212, v71, v212
	v_exp_f32_e32 v73, v73
	s_waitcnt lgkmcnt(3)
	v_mfma_f32_32x32x16_bf16 v[80:95], v[242:245], v[112:115], v[80:95]
	ds_read_b128 v[242:245], v192 offset:57344
	v_add_f32_e32 v212, v72, v212
	v_exp_f32_e32 v74, v74
	v_add_f32_e32 v212, v73, v212
	v_exp_f32_e32 v75, v75
	s_waitcnt lgkmcnt(3)
	v_mfma_f32_32x32x16_bf16 v[80:95], v[230:233], v[108:111], v[80:95]
	v_add_u32_e32 v211, 0x6000, v203
	ds_read_b128 v[230:233], v211 offset:49152
	v_add_f32_e32 v212, v74, v212
	v_exp_f32_e32 v76, v76
	v_add_f32_e32 v212, v75, v212
	v_exp_f32_e32 v77, v77
	s_waitcnt lgkmcnt(3)
	v_mfma_f32_32x32x16_bf16 v[80:95], v[234:237], v[104:107], v[80:95]
	v_add_u32_e32 v211, 0x6000, v204
	ds_read_b128 v[234:237], v211 offset:49152
	v_add_f32_e32 v212, v76, v212
	v_exp_f32_e32 v78, v78
	v_add_f32_e32 v212, v77, v212
	v_exp_f32_e32 v79, v79
	s_waitcnt lgkmcnt(3)
	v_mfma_f32_32x32x16_bf16 v[80:95], v[238:241], v[100:103], v[80:95]
	v_add_u32_e32 v211, 0x6000, v205
	ds_read_b128 v[238:241], v211 offset:49152
	v_add_f32_e32 v212, v78, v212
	v_add_f32_e32 v212, v79, v212
	v_mov_b32_e32 v213, v212
	s_waitcnt lgkmcnt(3)
	v_mfma_f32_32x32x16_bf16 v[80:95], v[242:245], v[96:99], v[80:95]
	v_add_u32_e32 v211, 0x6000, v206
	ds_read_b128 v[242:245], v211 offset:49152
	v_cvt_pk_bf16_f32 v152, v64, v65
	v_cvt_pk_bf16_f32 v153, v66, v67
	v_cvt_pk_bf16_f32 v154, v68, v69
	s_waitcnt lgkmcnt(3)
	v_mfma_f32_32x32x16_bf16 v[80:95], v[230:233], v[128:131], v[80:95]
	v_add_u32_e32 v211, v209, v194
	ds_read_b128 v[230:233], v211 offset:8192
	v_cvt_pk_bf16_f32 v155, v70, v71
	v_cvt_pk_bf16_f32 v156, v72, v73
	v_cvt_pk_bf16_f32 v157, v74, v75
	s_waitcnt lgkmcnt(3)
	v_mfma_f32_32x32x16_bf16 v[80:95], v[234:237], v[132:135], v[80:95]
	v_add_u32_e32 v211, v209, v195
	ds_read_b128 v[234:237], v211 offset:8192
	v_cvt_pk_bf16_f32 v158, v76, v77
	v_cvt_pk_bf16_f32 v159, v78, v79
	v_permlane32_swap_b32_e32 v212, v213
	s_waitcnt lgkmcnt(3)
	v_mfma_f32_32x32x16_bf16 v[80:95], v[238:241], v[136:139], v[80:95]
	v_add_u32_e32 v211, v209, v196
	ds_read_b128 v[238:241], v211 offset:8192
	v_add_f32_e32 v252, v212, v213
	v_fma_f32 v183, v207, v183, v252
	v_permlane32_swap_b32_e32 v152, v154
	s_waitcnt lgkmcnt(3)
	v_mfma_f32_32x32x16_bf16 v[80:95], v[242:245], v[140:143], v[80:95]
	v_add_u32_e32 v211, v209, v197
	ds_read_b128 v[242:245], v211 offset:8192
	v_permlane32_swap_b32_e32 v153, v155
	v_permlane32_swap_b32_e32 v156, v158
	v_permlane32_swap_b32_e32 v157, v159
	s_waitcnt lgkmcnt(3)
	v_mfma_f32_32x32x16_bf16 v[64:79], v[230:233], v[124:127], 0
	v_add_u32_e32 v211, v209, v198
	ds_read_b128 v[230:233], v211 offset:8192
	s_waitcnt lgkmcnt(3)
	v_mfma_f32_32x32x16_bf16 v[64:79], v[234:237], v[120:123], v[64:79]
	v_add_u32_e32 v211, v209, v199
	ds_read_b128 v[234:237], v211 offset:8192
	s_waitcnt lgkmcnt(3)
	v_mfma_f32_32x32x16_bf16 v[64:79], v[238:241], v[116:119], v[64:79]
	v_add_u32_e32 v211, v209, v200
	ds_read_b128 v[238:241], v211 offset:8192
	s_waitcnt lgkmcnt(3)
	v_mfma_f32_32x32x16_bf16 v[64:79], v[242:245], v[112:115], v[64:79]
	v_add_u32_e32 v211, v209, v201
	ds_read_b128 v[242:245], v211 offset:8192
	s_waitcnt lgkmcnt(3)
	v_mfma_f32_32x32x16_bf16 v[64:79], v[230:233], v[108:111], v[64:79]
	v_add_u32_e32 v211, 0x6000, v203
	ds_read_b128 v[230:233], v211 offset:53248
	s_waitcnt lgkmcnt(3)
	v_mfma_f32_32x32x16_bf16 v[64:79], v[234:237], v[104:107], v[64:79]
	v_add_u32_e32 v211, 0x6000, v204
	ds_read_b128 v[234:237], v211 offset:53248
	s_waitcnt lgkmcnt(3)
	v_mfma_f32_32x32x16_bf16 v[64:79], v[238:241], v[100:103], v[64:79]
	v_add_u32_e32 v211, 0x6000, v205
	ds_read_b128 v[238:241], v211 offset:53248
	v_max_f32_e32 v249, v80, v81
	v_max3_f32 v249, v249, v82, v83
	s_waitcnt lgkmcnt(3)
	v_mfma_f32_32x32x16_bf16 v[64:79], v[242:245], v[96:99], v[64:79]
	v_add_u32_e32 v211, 0x6000, v206
	ds_read_b128 v[242:245], v211 offset:53248
	v_max3_f32 v249, v249, v84, v85
	v_max3_f32 v249, v249, v86, v87
	s_waitcnt lgkmcnt(3)
	v_mfma_f32_32x32x16_bf16 v[64:79], v[230:233], v[128:131], v[64:79]
	ds_read_b64_tr_b16 v[214:215], v185
	ds_read_b64_tr_b16 v[216:217], v185 offset:2048
	v_max3_f32 v249, v249, v88, v89
	v_max3_f32 v249, v249, v90, v91
	s_waitcnt lgkmcnt(4)
	v_mfma_f32_32x32x16_bf16 v[64:79], v[234:237], v[132:135], v[64:79]
	ds_read_b64_tr_b16 v[218:219], v185 offset:4096
	ds_read_b64_tr_b16 v[220:221], v185 offset:6144
	v_max3_f32 v249, v249, v92, v93
	v_max3_f32 v249, v249, v94, v95
	s_waitcnt lgkmcnt(5)
	v_mfma_f32_32x32x16_bf16 v[64:79], v[238:241], v[136:139], v[64:79]
	ds_read_b64_tr_b16 v[222:223], v185 offset:8192
	ds_read_b64_tr_b16 v[224:225], v185 offset:10240
	s_waitcnt lgkmcnt(6)
	v_mfma_f32_32x32x16_bf16 v[64:79], v[242:245], v[140:143], v[64:79]
	ds_read_b64_tr_b16 v[226:227], v185 offset:12288
	ds_read_b64_tr_b16 v[228:229], v185 offset:14336
	s_waitcnt lgkmcnt(6)
	v_mfma_f32_32x32x16_bf16 v[0:15], v[144:147], v[214:217], v[0:15]
	ds_read_b64_tr_b16 v[214:215], v185 offset:512
	ds_read_b64_tr_b16 v[216:217], v185 offset:2560
	s_waitcnt lgkmcnt(6)
	v_mfma_f32_32x32x16_bf16 v[0:15], v[148:151], v[218:221], v[0:15]
	ds_read_b64_tr_b16 v[218:219], v185 offset:4608
	ds_read_b64_tr_b16 v[220:221], v185 offset:6656
	s_waitcnt lgkmcnt(6)
	v_mfma_f32_32x32x16_bf16 v[0:15], v[152:155], v[222:225], v[0:15]
	ds_read_b64_tr_b16 v[222:223], v185 offset:8704
	ds_read_b64_tr_b16 v[224:225], v185 offset:10752
	s_waitcnt lgkmcnt(6)
	v_mfma_f32_32x32x16_bf16 v[0:15], v[156:159], v[226:229], v[0:15]
	ds_read_b64_tr_b16 v[226:227], v185 offset:12800
	ds_read_b64_tr_b16 v[228:229], v185 offset:14848
	s_waitcnt lgkmcnt(6)
	v_mfma_f32_32x32x16_bf16 v[48:63], v[144:147], v[214:217], v[48:63]
	ds_read_b64_tr_b16 v[214:215], v185 offset:1024
	ds_read_b64_tr_b16 v[216:217], v185 offset:3072
	v_max3_f32 v249, v249, v64, v65
	v_max3_f32 v249, v249, v66, v67
	v_max3_f32 v249, v249, v68, v69
	v_max3_f32 v249, v249, v70, v71
	v_max3_f32 v249, v249, v72, v73
	v_max3_f32 v249, v249, v74, v75
	v_max3_f32 v249, v249, v76, v77
	v_max3_f32 v249, v249, v78, v79
	s_waitcnt lgkmcnt(6)
	v_mfma_f32_32x32x16_bf16 v[48:63], v[148:151], v[218:221], v[48:63]
	ds_read_b64_tr_b16 v[218:219], v185 offset:5120
	ds_read_b64_tr_b16 v[220:221], v185 offset:7168
	v_mov_b32_e32 v250, v249
	s_nop 1
	v_permlane32_swap_b32_e32 v249, v250
	v_max_f32_e32 v249, v249, v250
	v_sub_f32_e32 v250, v249, v208
	v_cmp_ge_f32_e32 vcc, s40, v250
	v_max_f32_e32 v249, v208, v249
	v_sub_f32_e32 v250, v208, v249
	s_waitcnt lgkmcnt(6)
	v_mfma_f32_32x32x16_bf16 v[48:63], v[152:155], v[222:225], v[48:63]
	ds_read_b64_tr_b16 v[222:223], v185 offset:9216
	ds_read_b64_tr_b16 v[224:225], v185 offset:11264
	v_mul_f32_e32 v250, 0x3dd53b94, v250
	v_exp_f32_e32 v250, v250
	s_cmp_eq_u64 vcc, exec
	s_cselect_b64 s[10:11], -1, 0
	v_cndmask_b32_e64 v207, v250, 1.0, s[10:11]
	v_cndmask_b32_e64 v208, v249, v208, s[10:11]
	v_mul_f32_e32 v251, 0xbdd53b94, v208
	v_fmamk_f32 v80, v80, 0x3dd53b94, v251
	s_waitcnt lgkmcnt(6)
	v_mfma_f32_32x32x16_bf16 v[48:63], v[156:159], v[226:229], v[48:63]
	ds_read_b64_tr_b16 v[226:227], v185 offset:13312
	ds_read_b64_tr_b16 v[228:229], v185 offset:15360
	v_fmamk_f32 v81, v81, 0x3dd53b94, v251
	v_fmamk_f32 v82, v82, 0x3dd53b94, v251
	v_fmamk_f32 v83, v83, 0x3dd53b94, v251
	v_fmamk_f32 v84, v84, 0x3dd53b94, v251
	v_fmamk_f32 v85, v85, 0x3dd53b94, v251
	v_fmamk_f32 v86, v86, 0x3dd53b94, v251
	v_fmamk_f32 v87, v87, 0x3dd53b94, v251
	s_waitcnt lgkmcnt(6)
	v_mfma_f32_32x32x16_bf16 v[32:47], v[144:147], v[214:217], v[32:47]
	ds_read_b64_tr_b16 v[214:215], v185 offset:1536
	ds_read_b64_tr_b16 v[216:217], v185 offset:3584
	v_fmamk_f32 v88, v88, 0x3dd53b94, v251
	v_fmamk_f32 v89, v89, 0x3dd53b94, v251
	v_fmamk_f32 v90, v90, 0x3dd53b94, v251
	v_fmamk_f32 v91, v91, 0x3dd53b94, v251
	v_fmamk_f32 v92, v92, 0x3dd53b94, v251
	v_fmamk_f32 v93, v93, 0x3dd53b94, v251
	v_fmamk_f32 v94, v94, 0x3dd53b94, v251
	s_waitcnt lgkmcnt(6)
	v_mfma_f32_32x32x16_bf16 v[32:47], v[148:151], v[218:221], v[32:47]
	ds_read_b64_tr_b16 v[218:219], v185 offset:5632
	ds_read_b64_tr_b16 v[220:221], v185 offset:7680
	v_fmamk_f32 v95, v95, 0x3dd53b94, v251
	v_exp_f32_e32 v80, v80
	v_fmamk_f32 v64, v64, 0x3dd53b94, v251
	v_exp_f32_e32 v81, v81
	v_fmamk_f32 v65, v65, 0x3dd53b94, v251
	v_add_f32_e32 v212, 0, v80
	v_exp_f32_e32 v82, v82
	s_waitcnt lgkmcnt(6)
	v_mfma_f32_32x32x16_bf16 v[32:47], v[152:155], v[222:225], v[32:47]
	ds_read_b64_tr_b16 v[222:223], v185 offset:9728
	ds_read_b64_tr_b16 v[224:225], v185 offset:11776
	v_fmamk_f32 v66, v66, 0x3dd53b94, v251
	v_add_f32_e32 v212, v81, v212
	v_exp_f32_e32 v83, v83
	v_fmamk_f32 v67, v67, 0x3dd53b94, v251
	v_add_f32_e32 v212, v82, v212
	v_exp_f32_e32 v84, v84
	v_fmamk_f32 v68, v68, 0x3dd53b94, v251
	s_waitcnt lgkmcnt(6)
	v_mfma_f32_32x32x16_bf16 v[32:47], v[156:159], v[226:229], v[32:47]
	ds_read_b64_tr_b16 v[226:227], v185 offset:13824
	ds_read_b64_tr_b16 v[228:229], v185 offset:15872
	v_add_f32_e32 v212, v83, v212
	v_exp_f32_e32 v85, v85
	v_fmamk_f32 v69, v69, 0x3dd53b94, v251
	v_add_f32_e32 v212, v84, v212
	v_exp_f32_e32 v86, v86
	v_fmamk_f32 v70, v70, 0x3dd53b94, v251
	v_add_f32_e32 v212, v85, v212
	s_waitcnt lgkmcnt(6)
	v_mfma_f32_32x32x16_bf16 v[16:31], v[144:147], v[214:217], v[16:31]
	v_exp_f32_e32 v87, v87
	v_fmamk_f32 v71, v71, 0x3dd53b94, v251
	v_add_f32_e32 v212, v86, v212
	v_exp_f32_e32 v88, v88
	v_fmamk_f32 v72, v72, 0x3dd53b94, v251
	v_add_f32_e32 v212, v87, v212
	v_exp_f32_e32 v89, v89
	s_waitcnt lgkmcnt(4)
	v_mfma_f32_32x32x16_bf16 v[16:31], v[148:151], v[218:221], v[16:31]
	v_fmamk_f32 v73, v73, 0x3dd53b94, v251
	v_add_f32_e32 v212, v88, v212
	v_exp_f32_e32 v90, v90
	v_fmamk_f32 v74, v74, 0x3dd53b94, v251
	v_add_f32_e32 v212, v89, v212
	v_exp_f32_e32 v91, v91
	v_fmamk_f32 v75, v75, 0x3dd53b94, v251
	s_waitcnt lgkmcnt(2)
	v_mfma_f32_32x32x16_bf16 v[16:31], v[152:155], v[222:225], v[16:31]
	v_add_f32_e32 v212, v90, v212
	v_exp_f32_e32 v92, v92
	v_fmamk_f32 v76, v76, 0x3dd53b94, v251
	v_add_f32_e32 v212, v91, v212
	v_exp_f32_e32 v93, v93
	v_fmamk_f32 v77, v77, 0x3dd53b94, v251
	v_add_f32_e32 v212, v92, v212
	s_waitcnt lgkmcnt(0)
	v_mfma_f32_32x32x16_bf16 v[16:31], v[156:159], v[226:229], v[16:31]
	v_exp_f32_e32 v94, v94
	v_fmamk_f32 v78, v78, 0x3dd53b94, v251
	v_add_f32_e32 v212, v93, v212
	v_exp_f32_e32 v95, v95
	v_fmamk_f32 v79, v79, 0x3dd53b94, v251
	v_add_f32_e32 v212, v94, v212
	v_add_f32_e32 v212, v95, v212
	v_cvt_pk_bf16_f32 v144, v80, v81
	v_cvt_pk_bf16_f32 v145, v82, v83
	v_cvt_pk_bf16_f32 v146, v84, v85
	v_cvt_pk_bf16_f32 v147, v86, v87
	v_cvt_pk_bf16_f32 v148, v88, v89
	v_cvt_pk_bf16_f32 v149, v90, v91
	v_cvt_pk_bf16_f32 v150, v92, v93
	v_cvt_pk_bf16_f32 v151, v94, v95
	v_permlane32_swap_b32_e32 v144, v146
	v_permlane32_swap_b32_e32 v145, v147
	v_permlane32_swap_b32_e32 v148, v150
	v_permlane32_swap_b32_e32 v149, v151
	v_cmp_gt_f32_e32 vcc, 1.0, v207
	s_cbranch_vccz .Lmla_noresc_t
	s_and_saveexec_b64 s[0:1], s[8:9]
	ds_write_b32 v182, v207 offset:128
	s_or_b64 exec, exec, s[0:1]
	s_waitcnt lgkmcnt(0)
	v_add_u32_e32 v253, s50, v181
	ds_read_b128 v[92:95], v253 offset:224
	ds_read_b128 v[88:91], v253 offset:192
	ds_read_b128 v[84:87], v253 offset:160
	ds_read_b128 v[80:83], v253 offset:128
	s_waitcnt lgkmcnt(3)
	v_pk_mul_f32 v[12:13], v[12:13], v[92:93]
	v_pk_mul_f32 v[14:15], v[14:15], v[94:95]
	v_pk_mul_f32 v[60:61], v[60:61], v[92:93]
	v_pk_mul_f32 v[62:63], v[62:63], v[94:95]
	v_pk_mul_f32 v[44:45], v[44:45], v[92:93]
	v_pk_mul_f32 v[46:47], v[46:47], v[94:95]
	v_pk_mul_f32 v[28:29], v[28:29], v[92:93]
	v_pk_mul_f32 v[30:31], v[30:31], v[94:95]
	s_waitcnt lgkmcnt(2)
	v_pk_mul_f32 v[8:9], v[8:9], v[88:89]
	v_pk_mul_f32 v[10:11], v[10:11], v[90:91]
	v_pk_mul_f32 v[56:57], v[56:57], v[88:89]
	v_pk_mul_f32 v[58:59], v[58:59], v[90:91]
	v_pk_mul_f32 v[40:41], v[40:41], v[88:89]
	v_pk_mul_f32 v[42:43], v[42:43], v[90:91]
	v_pk_mul_f32 v[24:25], v[24:25], v[88:89]
	v_pk_mul_f32 v[26:27], v[26:27], v[90:91]
	s_waitcnt lgkmcnt(1)
	v_pk_mul_f32 v[4:5], v[4:5], v[84:85]
	v_pk_mul_f32 v[6:7], v[6:7], v[86:87]
	v_pk_mul_f32 v[52:53], v[52:53], v[84:85]
	v_pk_mul_f32 v[54:55], v[54:55], v[86:87]
	v_pk_mul_f32 v[36:37], v[36:37], v[84:85]
	v_pk_mul_f32 v[38:39], v[38:39], v[86:87]
	v_pk_mul_f32 v[20:21], v[20:21], v[84:85]
	v_pk_mul_f32 v[22:23], v[22:23], v[86:87]
	s_waitcnt lgkmcnt(0)
	v_pk_mul_f32 v[0:1], v[0:1], v[80:81]
	v_pk_mul_f32 v[2:3], v[2:3], v[82:83]
	v_pk_mul_f32 v[48:49], v[48:49], v[80:81]
	v_pk_mul_f32 v[50:51], v[50:51], v[82:83]
	v_pk_mul_f32 v[32:33], v[32:33], v[80:81]
	v_pk_mul_f32 v[34:35], v[34:35], v[82:83]
	v_pk_mul_f32 v[16:17], v[16:17], v[80:81]
	v_pk_mul_f32 v[18:19], v[18:19], v[82:83]
